# v28: v17 with the grid-barrier spin-loop poll interval raised from s_sleep 1 to s_sleep 10 (fewer polling loads while waiting)
# speedup vs baseline: 1.0037x; 1.0009x over previous
.LBB0_90:
	flat_load_dword v26, v[2:3] offset:1024 sc1
	flat_load_dword v1, v[2:3] offset:1280 sc1
	flat_load_dword v12, v[2:3] offset:1536 sc1
	flat_load_dword v13, v[2:3] offset:1792 sc1
	flat_load_dword v14, v[2:3] offset:2048 sc1
	flat_load_dword v15, v[2:3] offset:2304 sc1
	flat_load_dword v16, v[2:3] offset:2560 sc1
	flat_load_dword v17, v[2:3] offset:2816 sc1
	flat_load_dword v18, v[2:3] offset:3072 sc1
	flat_load_dword v19, v[2:3] offset:3328 sc1
	flat_load_dword v20, v[2:3] offset:3584 sc1
	flat_load_dword v21, v[2:3] offset:3840 sc1
	flat_load_dword v22, v[4:5] sc1
	flat_load_dword v23, v[6:7] sc1
	flat_load_dword v24, v[8:9] sc1
	flat_load_dword v25, v[10:11] sc1
	s_or_b64 s[8:9], s[8:9], exec
	s_or_b64 s[6:7], s[6:7], exec
	s_waitcnt vmcnt(0) lgkmcnt(0)
	v_add_u32_e32 v27, v1, v26
	v_add_u32_e32 v27, v27, v12
	v_add_u32_e32 v27, v27, v13
	v_add_u32_e32 v27, v27, v14
	v_add_u32_e32 v27, v27, v15
	v_add_u32_e32 v27, v27, v16
	v_add_u32_e32 v27, v27, v17
	v_add_u32_e32 v27, v27, v18
	v_add_u32_e32 v27, v27, v19
	v_add_u32_e32 v27, v27, v20
	v_add_u32_e32 v27, v27, v21
	v_add_u32_e32 v27, v27, v22
	v_add_u32_e32 v27, v27, v23
	v_add_u32_e32 v27, v27, v24
	v_add_u32_e32 v27, v27, v25
	v_cmp_ne_u32_e32 vcc, s20, v27
	s_and_saveexec_b64 s[10:11], vcc
	s_cbranch_execz .LBB0_89
	s_and_b32 s14, s21, 0xff
	s_mov_b64 s[12:13], -1
	s_cmp_eq_u32 s14, 0
	s_mov_b64 s[16:17], -1
	s_mov_b64 s[14:15], -1
	s_sleep 10
	s_cbranch_scc1 .LBB0_93
	s_and_saveexec_b64 s[18:19], s[16:17]
	s_cbranch_execz .LBB0_88
	s_branch .LBB0_96

.LBB0_104:
	s_and_b32 s16, s23, 0xff
	s_mov_b64 s[14:15], -1
	s_cmp_lg_u32 s16, 0
	s_mov_b64 s[16:17], -1
	s_sleep 10
	s_cbranch_scc1 .LBB0_108
	v_mov_b64_e32 v[2:3], s[24:25]
	flat_load_dword v2, v[2:3] offset:512 sc1
	s_mov_b64 s[16:17], 0
	s_mov_b64 s[18:19], -1
	s_waitcnt vmcnt(0) lgkmcnt(0)
	v_cmp_eq_u32_e32 vcc, 0, v2
	s_and_saveexec_b64 s[20:21], vcc
	s_cmp_lt_u32 s23, 0x40001
	s_cselect_b64 s[16:17], -1, 0
	s_xor_b64 s[18:19], exec, -1
	s_and_b64 s[16:17], s[16:17], exec
	s_or_b64 exec, exec, s[20:21]

.LBB0_118:
	s_and_b32 s14, s23, 0xff
	s_cmp_lg_u32 s14, 0
	s_mov_b64 s[16:17], -1
	s_sleep 10
	s_cbranch_scc0 .LBB0_120
	s_mov_b64 s[18:19], -1
	s_and_saveexec_b64 s[20:21], s[16:17]
	s_cbranch_execz .LBB0_117
	s_branch .LBB0_123

.LBB0_511:
	v_mov_b64_e32 v[14:15], s[24:25]
	flat_load_dword v3, v[14:15] offset:1024 sc1
	flat_load_dword v2, v[14:15] offset:1280 sc1
	flat_load_dword v4, v[14:15] offset:1536 sc1
	s_or_b64 s[18:19], s[18:19], exec
	s_or_b64 s[16:17], s[16:17], exec
	s_waitcnt vmcnt(0) lgkmcnt(0)
	v_add_u32_e32 v5, v2, v3
	v_add_u32_e32 v6, v5, v4
	flat_load_dword v5, v[14:15] offset:1792 sc1
	s_waitcnt vmcnt(0) lgkmcnt(0)
	v_add_u32_e32 v7, v6, v5
	flat_load_dword v6, v[14:15] offset:2048 sc1
	s_waitcnt vmcnt(0) lgkmcnt(0)
	v_add_u32_e32 v8, v7, v6
	flat_load_dword v7, v[14:15] offset:2304 sc1
	s_waitcnt vmcnt(0) lgkmcnt(0)
	v_add_u32_e32 v9, v8, v7
	flat_load_dword v8, v[14:15] offset:2560 sc1
	s_waitcnt vmcnt(0) lgkmcnt(0)
	v_add_u32_e32 v10, v9, v8
	flat_load_dword v9, v[14:15] offset:2816 sc1
	s_waitcnt vmcnt(0) lgkmcnt(0)
	v_add_u32_e32 v11, v10, v9
	flat_load_dword v10, v[14:15] offset:3072 sc1
	s_waitcnt vmcnt(0) lgkmcnt(0)
	v_add_u32_e32 v12, v11, v10
	flat_load_dword v11, v[14:15] offset:3328 sc1
	s_waitcnt vmcnt(0) lgkmcnt(0)
	v_add_u32_e32 v13, v12, v11
	flat_load_dword v12, v[14:15] offset:3584 sc1
	s_waitcnt vmcnt(0) lgkmcnt(0)
	v_add_u32_e32 v16, v13, v12
	flat_load_dword v13, v[14:15] offset:3840 sc1
	v_mov_b64_e32 v[14:15], s[4:5]
	flat_load_dword v14, v[14:15] sc1
	s_waitcnt vmcnt(0) lgkmcnt(0)
	v_add_u32_e32 v16, v16, v13
	v_add_u32_e32 v18, v16, v14
	v_mov_b64_e32 v[16:17], s[6:7]
	flat_load_dword v15, v[16:17] sc1
	v_mov_b64_e32 v[16:17], s[8:9]
	flat_load_dword v16, v[16:17] sc1
	s_waitcnt vmcnt(0) lgkmcnt(0)
	v_add_u32_e32 v18, v18, v15
	v_add_u32_e32 v20, v18, v16
	v_mov_b64_e32 v[18:19], s[10:11]
	flat_load_dword v17, v[18:19] sc1
	s_waitcnt vmcnt(0) lgkmcnt(0)
	v_add_u32_e32 v18, v20, v17
	v_cmp_ne_u32_e32 vcc, s30, v18
	s_and_saveexec_b64 s[0:1], vcc
	s_cbranch_execz .LBB0_510
	s_and_b32 s22, s31, 0xff
	s_mov_b64 s[20:21], -1
	s_cmp_eq_u32 s22, 0
	s_mov_b64 s[26:27], -1
	s_mov_b64 s[22:23], -1
	s_sleep 10
	s_cbranch_scc1 .LBB0_514
	s_and_saveexec_b64 s[28:29], s[26:27]
	s_cbranch_execz .LBB0_509
	s_branch .LBB0_517

.LBB0_525:
	s_and_b32 s16, s23, 0xff
	s_mov_b64 s[14:15], -1
	s_cmp_lg_u32 s16, 0
	s_mov_b64 s[16:17], -1
	s_sleep 10
	s_cbranch_scc1 .LBB0_529
	v_mov_b64_e32 v[4:5], s[24:25]
	flat_load_dword v2, v[4:5] offset:512 sc1
	s_mov_b64 s[16:17], 0
	s_mov_b64 s[18:19], -1
	s_waitcnt vmcnt(0) lgkmcnt(0)
	v_cmp_eq_u32_e32 vcc, 0, v2
	s_and_saveexec_b64 s[20:21], vcc
	s_cmp_lt_u32 s23, 0x40001
	s_cselect_b64 s[16:17], -1, 0
	s_xor_b64 s[18:19], exec, -1
	s_and_b64 s[16:17], s[16:17], exec
	s_or_b64 exec, exec, s[20:21]

.LBB0_539:
	s_and_b32 s16, s23, 0xff
	s_mov_b64 s[14:15], -1
	s_cmp_lg_u32 s16, 0
	s_mov_b64 s[18:19], -1
	s_sleep 10
	s_cbranch_scc0 .LBB0_541
	s_and_saveexec_b64 s[20:21], s[18:19]
	s_cbranch_execz .LBB0_538
	s_branch .LBB0_544
